# grid barrier: non-returning arrival atomics, a designated per-XCD leader (census rank 0) waits for local arrivals, everyone polls the cross-XCD counter
# speedup vs baseline: 1.0047x; 1.0047x over previous
.LBB0_1:
	v_and_b32_e32 v191, 0x3ff, v0
	v_cmp_gt_u32_e32 vcc, 4, v191
	s_and_saveexec_b64 s[4:5], vcc

.LBB0_3:
	s_or_b64 exec, exec, s[4:5]
	s_waitcnt lgkmcnt(0)
	s_barrier
	s_getreg_b32 s2, hwreg(HW_REG_XCC_ID, 0, 4)
	v_cmp_eq_u32_e64 s[6:7], 0, v191
	s_mov_b64 s[4:5], exec
	s_nop 0
	v_writelane_b32 v254, s6, 4
	s_nop 1
	v_writelane_b32 v254, s7, 5
	s_and_b64 s[6:7], s[4:5], s[6:7]
	s_mov_b64 exec, s[6:7]
	s_cbranch_execz .LBB0_6
	s_mov_b64 s[6:7], exec
	v_mbcnt_lo_u32_b32 v1, s6, 0
	v_mbcnt_hi_u32_b32 v1, s7, v1
	v_cmp_eq_u32_e32 vcc, 0, v1
	s_and_b64 s[8:9], exec, vcc
	s_mov_b64 exec, s[8:9]
	s_cbranch_execz .LBB0_6
	s_load_dwordx2 s[8:9], s[0:1], 0xc8
	s_lshl_b32 s2, s2, 8
	s_and_b32 s2, s2, 0xf00
	s_bcnt1_i32_b64 s3, s[6:7]
	v_mov_b32_e32 v1, s2
	v_mov_b32_e32 v2, s3
	s_waitcnt lgkmcnt(0)
	global_atomic_add v2, v1, v2, s[8:9] offset:1024 sc0
	v_mov_b32_e32 v1, 0x23fc8
	s_waitcnt vmcnt(0)
	ds_write_b32 v1, v2
	s_waitcnt lgkmcnt(0)

.LBB0_31:
	s_lshl_b32 s3, s3, 8
	s_add_u32 s10, s6, s3
	s_addc_u32 s11, s7, 0
	v_mov_b32_e32 v0, 0x23fc8
	ds_read2_b32 v[4:5], v0 offset1:1
	v_mov_b32_e32 v6, 1
	v_mov_b32_e32 v7, 0x1000
	global_atomic_add v7, v6, s[10:11] offset:1024
	s_waitcnt lgkmcnt(0)
	v_add_u32_e32 v8, 1, v5
	v_mov_b32_e32 v9, 0x23fcc
	ds_write_b32 v9, v8
	v_mul_lo_u32 v10, v8, v3
	v_mul_lo_u32 v11, v8, v2
	v_cmp_ne_u32_e32 vcc, 0, v4
	s_cbranch_vccnz .Lnb_poll_top_r
	s_mov_b32 s3, 0
.Lnb_spin_loc_r:
	global_load_dword v6, v7, s[10:11] offset:1024 sc1
	s_waitcnt vmcnt(0)
	v_cmp_le_u32_e32 vcc, v10, v6
	s_cbranch_vccnz .Lnb_loc_done_r
	s_sleep 1
	s_add_i32 s3, s3, 1
	s_cmp_lt_u32 s3, 0x40000
	s_cbranch_scc1 .Lnb_spin_loc_r
.Lnb_loc_done_r:
	buffer_wbl2 sc1
	s_waitcnt vmcnt(0)
	v_mov_b32_e32 v6, 1
	v_mov_b32_e32 v12, 0x3400
	global_atomic_add v12, v6, s[6:7]
.Lnb_poll_top_r:
	v_mov_b32_e32 v12, 0x3400
	s_mov_b32 s3, 0
.Lnb_spin_top_r:
	global_load_dword v6, v12, s[6:7] sc1
	s_waitcnt vmcnt(0)
	v_cmp_le_u32_e32 vcc, v11, v6
	s_cbranch_vccnz .Lnb_done_r
	s_sleep 1
	s_add_i32 s3, s3, 1
	s_cmp_lt_u32 s3, 0x40000
	s_cbranch_scc1 .Lnb_spin_top_r
.Lnb_done_r:
	buffer_inv sc1
	s_waitcnt vmcnt(0)

.LBB0_664:
	s_lshl_b32 s2, s2, 8
	s_add_u32 s10, s6, s2
	s_addc_u32 s11, s7, 0
	v_mov_b32_e32 v0, 0x23fc8
	ds_read2_b32 v[4:5], v0 offset1:1
	v_mov_b32_e32 v6, 1
	v_mov_b32_e32 v7, 0x1000
	global_atomic_add v7, v6, s[10:11] offset:1024
	s_waitcnt lgkmcnt(0)
	v_add_u32_e32 v8, 1, v5
	v_mov_b32_e32 v9, 0x23fcc
	ds_write_b32 v9, v8
	v_mul_lo_u32 v10, v8, v3
	v_mul_lo_u32 v11, v8, v2
	v_cmp_ne_u32_e32 vcc, 0, v4
	s_cbranch_vccnz .Lnb_poll_top_m
	s_mov_b32 s2, 0
.Lnb_spin_loc_m:
	global_load_dword v6, v7, s[10:11] offset:1024 sc1
	s_waitcnt vmcnt(0)
	v_cmp_le_u32_e32 vcc, v10, v6
	s_cbranch_vccnz .Lnb_loc_done_m
	s_sleep 1
	s_add_i32 s2, s2, 1
	s_cmp_lt_u32 s2, 0x40000
	s_cbranch_scc1 .Lnb_spin_loc_m

.Lnb_poll_top_m:
	v_mov_b32_e32 v12, 0x3400
	s_mov_b32 s2, 0
.Lnb_spin_top_m:
	global_load_dword v6, v12, s[6:7] sc1
	s_waitcnt vmcnt(0)
	v_cmp_le_u32_e32 vcc, v11, v6
	s_cbranch_vccnz .Lnb_done_m
	s_sleep 1
	s_add_i32 s2, s2, 1
	s_cmp_lt_u32 s2, 0x40000
	s_cbranch_scc1 .Lnb_spin_top_m

.LBB0_712:
	v_readlane_b32 s5, v254, 2
	s_ashr_i32 s3, s5, 31
	s_lshr_b32 s3, s3, 29
	s_add_i32 s3, s5, s3
	s_and_b32 s4, s3, -8
	s_ashr_i32 s2, s81, 3
	s_sub_i32 s4, s5, s4
	s_mul_i32 s2, s2, s4
	s_ashr_i32 s3, s3, 3
	s_add_i32 s2, s2, s3
	v_writelane_b32 v254, s2, 3
	v_and_b32_e32 v191, 0x3ff, v0
	v_cmp_gt_u32_e32 vcc, 4, v191
	s_and_saveexec_b64 s[4:5], vcc
	s_cbranch_execz .LBB0_715
	s_getpc_b64 s[98:99]
